# m1+m2: single 16B row-stat slot load; down-projection phases merged (one grid barrier less per layer)
# speedup vs baseline: 1.0819x; 1.0819x over previous
;     __device__ __forceinline__ void run(const pg8::f32x4 (&v)[2][2][4][2], const pg8::Unit& u, int wr, int wc, int fr, int fq, LAS unsigned char* lds, int wid, int lane) const {
;     ...
;         asm volatile("s_waitcnt lgkmcnt(0)" ::: "memory"); __builtin_amdgcn_s_barrier(); asm volatile("" ::: "memory");
;         const int row = wid * 32 + (lane & 31);
;         if (lane < 32) {
;             const float t = (P[row * 4 + 0] + P[row * 4 + 1]) + (P[row * 4 + 2] + P[row * 4 + 3]);
;             __hip_atomic_store(xbuf + ((size_t)(u.pm * 256 + row) * 4 + u.pn), t, __ATOMIC_RELAXED, __HIP_MEMORY_SCOPE_AGENT);
;         }
;     __device__ __forceinline__ void fused(pg8::f32x4 (&acc)[2][2][4][2], const pg8::Unit& u, int wr, int wc, int fr, int fq, LAS unsigned char* lds, int wid, int lane) const {
;     ...
;         const RowStat st{(float*)(ws + WS_XB), (unsigned*)(ws + WS_CNT) + (size_t)(8 + l * 2 + b) * 4096};
.LBB0_207:
	s_or_b64 exec, exec, s[6:7]
	v_and_b32_e32 v192, 31, v210
	s_waitcnt lgkmcnt(0)
	s_barrier
	v_lshl_or_b32 v192, s2, 5, v192
	s_add_u32 s16, s10, 0x140000
	v_add_u32_e32 v220, s18, v192
	s_addc_u32 s17, s11, 0
	s_lshl_b32 s98, s52, 18
	s_add_u32 s16, s16, s98
	s_addc_u32 s17, s17, 0
	v_cmp_gt_u32_e64 s[6:7], 32, v211
	s_waitcnt lgkmcnt(0)
	v_ashrrev_i32_e32 v221, 31, v220
	s_and_saveexec_b64 s[18:19], s[6:7]
	s_cbranch_execz .LBB0_209
	v_lshl_add_u32 v194, v192, 4, 0
	ds_read_b128 v[232:235], v194
	s_ashr_i32 s15, s14, 31
	v_lshl_add_u64 v[196:197], v[220:221], 4, s[16:17]
	v_lshl_add_u64 v[196:197], s[14:15], 2, v[196:197]
	s_waitcnt lgkmcnt(0)
	v_mov_b32_e32 v194, v233
	v_mov_b32_e32 v195, v234
	v_mov_b32_e32 v233, v235
	v_pk_add_f32 v[194:195], v[194:195], v[232:233]
	s_nop 0
	v_pk_add_f32 v[194:195], v[194:195], v[194:195] op_sel:[0,1] op_sel_hi:[1,0]
	global_store_dword v[196:197], v194, off sc1

;     __device__ __forceinline__ void run(const pg8::f32x4 (&v)[2][2][4][2], const pg8::Unit& u, int wr, int wc, int fr, int fq, LAS unsigned char* lds, int wid, int lane) const {
;     ...
;         asm volatile("s_waitcnt vmcnt(0) lgkmcnt(0)" ::: "memory"); __builtin_amdgcn_s_barrier(); asm volatile("" ::: "memory");
;         if (lane < 32) {
;             const float* slot = xbuf + (size_t)(u.pm * 256 + row) * 4; float tot = 0.f;
; #pragma unroll
;             for (int t = 0; t < 4; ++t) tot += __hip_atomic_load(slot + t, __ATOMIC_RELAXED, __HIP_MEMORY_SCOPE_AGENT);
;             S[row] = rsqrtf(tot * (1.f / D) + EPS);
;         }
.LBB0_218:
	s_waitcnt vmcnt(0) lgkmcnt(0)
	s_barrier
	s_and_saveexec_b64 s[14:15], s[6:7]
	s_cbranch_execz .LBB0_220
	v_lshl_add_u64 v[194:195], v[220:221], 4, s[16:17]
	global_load_dwordx4 v[240:243], v[194:195], off sc1
	v_lshl_add_u32 v192, v192, 2, 0
	s_waitcnt vmcnt(0)
	v_add_f32_e32 v196, 0, v240
	v_add_f32_e32 v196, v196, v241
	v_add_f32_e32 v196, v196, v242
	v_add_f32_e32 v194, v196, v243
	v_fmamk_f32 v194, v194, 0x3a800000, v223
	v_cmp_gt_f32_e32 vcc, s24, v194
	v_mul_f32_e32 v195, 0x4b800000, v194
	s_nop 0
	v_cndmask_b32_e32 v194, v194, v195, vcc
	v_rsq_f32_e32 v194, v194
	s_nop 0
	v_mul_f32_e32 v195, 0x45800000, v194
	v_cndmask_b32_e32 v194, v194, v195, vcc
	ds_write_b32 v192, v194 offset:8192

;     __device__ __forceinline__ void run(const pg8::f32x4 (&v)[2][2][4][2], const pg8::Unit& u, int wr, int wc, int fr, int fq, LAS unsigned char* lds, int wid, int lane) const {
;     ...
;         asm volatile("s_waitcnt vmcnt(0) lgkmcnt(0)" ::: "memory"); __builtin_amdgcn_s_barrier(); asm volatile("" ::: "memory");
;         if (lane < 32) {
;             const float* slot = xbuf + (size_t)(u.pm * 256 + row) * 4; float tot = 0.f;
; #pragma unroll
;             for (int t = 0; t < 4; ++t) tot += __hip_atomic_load(slot + t, __ATOMIC_RELAXED, __HIP_MEMORY_SCOPE_AGENT);
;             S[row] = rsqrtf(tot * (1.f / D) + EPS);
;         }
.LBB0_273:
	s_waitcnt vmcnt(0) lgkmcnt(0)
	s_barrier
	v_lshl_add_u32 v234, v218, 2, 0
	s_and_saveexec_b64 s[52:53], s[8:9]
	s_cbranch_execz .LBB0_275
	v_lshl_add_u64 v[194:195], v[216:217], 4, s[58:59]
	global_load_dwordx4 v[202:205], v[194:195], off sc1
	s_waitcnt vmcnt(0)
	v_add_f32_e32 v196, 0, v202
	v_add_f32_e32 v196, v196, v203
	v_add_f32_e32 v196, v196, v204
	v_add_f32_e32 v194, v196, v205
	v_fmamk_f32 v194, v194, 0x3a800000, v223
	v_cmp_gt_f32_e32 vcc, s24, v194
	v_mul_f32_e32 v195, 0x4b800000, v194
	s_nop 0
	v_cndmask_b32_e32 v194, v194, v195, vcc
	v_rsq_f32_e32 v194, v194
	s_nop 0
	v_mul_f32_e32 v195, 0x45800000, v194
	v_cndmask_b32_e32 v194, v194, v195, vcc
	ds_write_b32 v234, v194 offset:8192

;     __device__ __forceinline__ void run(const pg8::f32x4 (&v)[2][2][4][2], const pg8::Unit& u, int wr, int wc, int fr, int fq, LAS unsigned char* lds, int wid, int lane) const {
;     ...
;         asm volatile("s_waitcnt vmcnt(0) lgkmcnt(0)" ::: "memory"); __builtin_amdgcn_s_barrier(); asm volatile("" ::: "memory");
;         if (lane < 32) {
;             const float* slot = xbuf + (size_t)(u.pm * 256 + row) * 4; float tot = 0.f;
; #pragma unroll
;             for (int t = 0; t < 4; ++t) tot += __hip_atomic_load(slot + t, __ATOMIC_RELAXED, __HIP_MEMORY_SCOPE_AGENT);
;             S[row] = rsqrtf(tot * (1.f / D) + EPS);
;         }
.LBB0_302:
	s_waitcnt vmcnt(0) lgkmcnt(0)
	s_barrier
	s_and_saveexec_b64 s[10:11], s[8:9]
	s_cbranch_execz .LBB0_304
	s_waitcnt lgkmcnt(0)
	v_lshl_add_u64 v[128:129], v[216:217], 4, s[6:7]
	global_load_dwordx4 v[236:239], v[128:129], off sc1
	s_waitcnt vmcnt(0)
	v_add_f32_e32 v130, 0, v236
	v_add_f32_e32 v130, v130, v237
	v_add_f32_e32 v130, v130, v238
	v_add_f32_e32 v128, v130, v239
	v_fmamk_f32 v128, v128, 0x3a800000, v223
	v_cmp_gt_f32_e32 vcc, s24, v128
	v_mul_f32_e32 v129, 0x4b800000, v128
	s_nop 0
	v_cndmask_b32_e32 v128, v128, v129, vcc
	v_rsq_f32_e32 v128, v128
	s_nop 0
	v_mul_f32_e32 v129, 0x45800000, v128
	v_cndmask_b32_e32 v128, v128, v129, vcc
	ds_write_b32 v234, v128 offset:8192

; #define LAS __attribute__((address_space(3)))
; __device__ __forceinline__ unsigned xb_xcc_id() { return (unsigned)__builtin_amdgcn_s_getreg((3 << 11) | 20) & 0xFu; }
; __global__ void __launch_bounds__(512, 2) mega(Args a) {
;     ...
;         if (st + 1 >= ka->ph_hi) break;
;         if (ka->ph_lo < 0) cg::this_grid().sync();
;         else { XcdBarrier xb; xb.bar = (unsigned*)(ka->ws + WS_BAR); xb.x = xb_xcc_id(); xb.st = (volatile LAS unsigned*)(lds + LDS_ST); xcd_barrier(xb); }
;         ++st;
.LBB0_722:
	s_load_dword s1, s[66:67], 0xc4
	s_add_i32 s0, s3, 1
	s_mov_b32 s2, 2
	s_waitcnt lgkmcnt(0)
	s_cmp_ge_i32 s0, s1
	s_mov_b32 s1, s3
	s_cbranch_scc1 .LBB0_790
	s_load_dword s1, s[66:67], 0xc0
	s_mov_b64 s[6:7], -1
	s_waitcnt lgkmcnt(0)
	s_cmp_gt_i32 s1, -1
	s_cbranch_scc0 .LBB0_777
	s_cmp_eq_u32 s3, 15
	s_cbranch_scc1 .Lskipbar
	s_cmp_lg_u32 s3, 33
	s_cbranch_scc1 .Lnoskip
.Lskipbar:
	s_waitcnt vmcnt(0) lgkmcnt(0)
	s_barrier
	s_branch .LBB0_789
.Lnoskip:
	s_getreg_b32 s1, hwreg(HW_REG_XCC_ID, 0, 4)
	s_waitcnt vmcnt(0)
	s_waitcnt vmcnt(0)
	s_barrier
	s_and_saveexec_b64 s[6:7], s[94:95]
	s_cbranch_execz .LBB0_776
	v_readlane_b32 s2, v255, 10
	s_waitcnt vmcnt(0) expcnt(0) lgkmcnt(0)
	s_and_b32 s1, s1, 15
	v_mov_b32_e32 v0, s2
	ds_read_b32 v2, v0
	v_readlane_b32 s2, v255, 11
	s_waitcnt lgkmcnt(0)
	v_cmp_ne_u32_e32 vcc, 0, v2
	v_mov_b32_e32 v0, s2
	ds_read_b32 v0, v0
	s_cbranch_vccnz .LBB0_740
	s_load_dwordx2 s[12:13], s[96:97], 0x4
	s_add_u32 s8, s30, 0x80200
	s_addc_u32 s9, s31, 0
	s_add_u32 s10, s30, 0x80400
	s_addc_u32 s11, s31, 0
	s_waitcnt lgkmcnt(0)
	s_mul_i32 s2, s12, s75
	s_add_u32 s12, s30, 0x80500
	s_mul_i32 s2, s2, s13
	s_addc_u32 s13, s31, 0
	s_add_u32 s14, s30, 0x80600
	s_addc_u32 s15, s31, 0
	s_add_u32 s16, s30, 0x80700
	s_addc_u32 s17, s31, 0
	s_add_u32 s18, s30, 0x80800
	s_addc_u32 s19, s31, 0
	s_add_u32 s20, s30, 0x80900
	s_addc_u32 s21, s31, 0
	s_add_u32 s22, s30, 0x80a00
	s_addc_u32 s23, s31, 0
	s_add_u32 s28, s30, 0x80b00
	s_addc_u32 s29, s31, 0
	s_add_u32 s44, s30, 0x80c00
	s_addc_u32 s45, s31, 0
	s_add_u32 s58, s30, 0x80d00
	s_addc_u32 s59, s31, 0
	s_add_u32 s66, s30, 0x80e00
	s_addc_u32 s67, s31, 0
	s_add_u32 s68, s30, 0x80f00
	s_addc_u32 s69, s31, 0
	s_add_u32 s70, s30, 0x81000
	s_addc_u32 s71, s31, 0
	s_add_u32 s72, s30, 0x81100
	s_addc_u32 s73, s31, 0
	s_add_u32 s74, s30, 0x81200
	s_addc_u32 s75, s31, 0
	s_add_u32 s76, s30, 0x81300
	s_addc_u32 s77, s31, 0
	s_mov_b32 s26, 1
	s_branch .LBB0_728
